# GEMM1 k-loops: LDS ring 3->4 stages, LDS-DMA issued 3 k-steps ahead (two stages in flight across the closing barrier)
# speedup vs baseline: 1.0068x; 1.0007x over previous
.LBB0_118:
	s_andn2_b64 vcc, exec, s[0:1]
	s_cbranch_vccnz .LBB0_389
	s_lshl_b32 s80, s2, 26
	v_mov_b32_e32 v1, v228
	s_add_u32 s6, s74, s80
	s_addc_u32 s7, s75, 0
	v_readfirstlane_b32 s2, v1
	s_ashr_i32 s1, s2, 6
	s_lshl_b32 s0, s1, 4
	v_bfe_u32 v0, v1, 2, 4
	v_bfe_u32 v2, v1, 4, 2
	v_or_b32_e32 v6, s0, v0
	v_sub_u32_e32 v3, 0, v2
	v_add_u32_e32 v4, s19, v6
	v_xor_b32_e32 v3, v1, v3
	v_ashrrev_i32_e32 v5, 31, v4
	v_readlane_b32 s3, v253, 39
	v_lshlrev_b64 v[4:5], 11, v[4:5]
	v_lshlrev_b32_e32 v7, 4, v3
	v_add_u32_e32 v6, s3, v6
	v_lshl_add_u64 v[4:5], s[6:7], 0, v[4:5]
	v_and_b32_e32 v176, 48, v7
	v_ashrrev_i32_e32 v7, 31, v6
	v_readlane_b32 s6, v253, 34
	v_readlane_b32 s8, v253, 36
	v_lshlrev_b64 v[6:7], 11, v[6:7]
	v_readlane_b32 s7, v253, 35
	s_lshl_b32 s15, s1, 10
	v_readlane_b32 s9, v253, 37
	v_lshl_add_u64 v[4:5], v[4:5], 0, v[176:177]
	v_lshl_add_u64 v[6:7], s[6:7], 0, v[6:7]
	s_mov_b32 m0, s15
	s_load_dword s14, s[8:9], 0x0
	s_waitcnt vmcnt(0)
	s_waitcnt lgkmcnt(0)
	s_barrier
	v_lshl_add_u64 v[6:7], v[6:7], 0, v[176:177]
	global_load_lds_dwordx4 v[4:5], off
	s_add_i32 m0, s15, 0x4000
	v_lshl_add_u64 v[8:9], v[4:5], 0, s[94:95]
	global_load_lds_dwordx4 v[6:7], off
	s_add_i32 m0, s15, 0x2000
	v_lshl_add_u64 v[10:11], v[6:7], 0, 64
	global_load_lds_dwordx4 v[8:9], off
	v_lshl_add_u64 v[8:9], v[6:7], 0, s[94:95]
	s_add_i32 m0, s15, 0x6000
	s_mov_b64 s[6:7], 0x40040
	global_load_lds_dwordx4 v[8:9], off
	v_lshl_add_u64 v[8:9], v[4:5], 0, 64
	s_add_i32 m0, s15, 0x8000
	v_lshl_add_u64 v[4:5], v[4:5], 0, s[6:7]
	global_load_lds_dwordx4 v[8:9], off
	s_add_i32 m0, s15, 0x10000
	v_lshl_add_u64 v[12:13], v[8:9], 0, 64
	global_load_lds_dwordx4 v[12:13], off
	s_add_i32 m0, s15, 0xc000
	s_nop 0
	global_load_lds_dwordx4 v[10:11], off
	s_add_i32 m0, s15, 0x14000
	v_lshl_add_u64 v[12:13], v[10:11], 0, 64
	global_load_lds_dwordx4 v[12:13], off
	s_add_i32 m0, s15, 0xa000
	s_nop 0
	global_load_lds_dwordx4 v[4:5], off
	s_add_i32 m0, s15, 0x12000
	v_lshl_add_u64 v[12:13], v[4:5], 0, 64
	global_load_lds_dwordx4 v[12:13], off
	v_lshl_add_u64 v[4:5], v[6:7], 0, s[6:7]
	s_add_i32 m0, s15, 0x16000
	v_lshl_add_u64 v[12:13], v[4:5], 0, 64
	global_load_lds_dwordx4 v[12:13], off
	s_add_i32 m0, s15, 0xe000
	s_cmpk_gt_u32 s2, 0xff
	global_load_lds_dwordx4 v[4:5], off
	s_waitcnt vmcnt(4)
	s_cselect_b64 s[38:39], -1, 0
	s_cmpk_lt_u32 s2, 0x100
	s_waitcnt vmcnt(0) lgkmcnt(0)
	s_barrier
	s_cbranch_scc1 .LBB0_121
	s_setprio 1
.LBB0_121:
	s_lshr_b32 s16, s14, 3
	s_ashr_i32 s2, s2, 8
	s_and_b32 s3, s1, 3
	s_add_i32 s6, s16, s25
	s_cmp_gt_u32 s6, 31
	v_and_b32_e32 v4, 15, v1
	v_lshrrev_b32_e32 v5, 2, v1
	s_cselect_b32 s21, s25, s6
	v_readlane_b32 s6, v252, 39
	v_readlane_b32 s7, v253, 40
	v_lshlrev_b32_e32 v213, 2, v2
	v_and_b32_e32 v1, 16, v1
	s_cselect_b32 s17, s7, s6
	s_lshl_b32 s41, s1, 12
	v_and_or_b32 v215, v213, 8, v1
	v_and_b32_e32 v1, 3, v3
	v_add_u32_e32 v216, s0, v0
	v_readlane_b32 s0, v252, 44
	v_lshlrev_b32_e32 v176, 4, v1
	v_readlane_b32 s1, v252, 45
	v_sub_u32_e32 v5, 0, v5
	v_bitop3_b32 v5, v2, v5, 3 bitop3:0x78
	v_lshl_add_u64 v[180:181], s[0:1], 0, v[176:177]
	v_readlane_b32 s0, v252, 46
	v_lshl_add_u64 v[2:3], s[80:81], 0, v[176:177]
	v_readlane_b32 s1, v252, 47
	s_lshl_b32 s20, s2, 13
	s_lshl_b32 s40, s3, 12
	s_lshl_b32 s50, s3, 6
	v_lshl_or_b32 v214, s2, 7, v4
	v_readlane_b32 s2, v252, 42
	v_lshl_add_u64 v[182:183], s[0:1], 0, v[2:3]
	v_readlane_b32 s0, v252, 48
	v_readlane_b32 s3, v252, 43
	v_readlane_b32 s1, v252, 49
	s_mov_b32 s52, 0
	v_lshlrev_b32_e32 v211, 4, v5
	v_lshlrev_b32_e32 v212, 6, v4
	v_lshl_add_u64 v[178:179], s[2:3], 0, v[2:3]
	v_lshl_add_u64 v[184:185], s[0:1], 0, v[176:177]
	s_mov_b32 s51, 0
	s_mov_b32 s18, 0
	v_readlane_b32 s6, v253, 39
	s_mov_b32 s48, s19
	s_movk_i32 s24, 0x7ff
	v_lshl_add_u64 v[178:179], v[178:179], 0, 64
	v_lshl_add_u64 v[180:181], v[180:181], 0, 64
	v_lshl_add_u64 v[182:183], v[182:183], 0, 64
	v_lshl_add_u64 v[184:185], v[184:185], 0, 64
	s_branch .LBB0_123

.LBB0_127:
	s_add_i32 s0, s7, 1
	s_cmp_lg_u32 s7, 3
	s_waitcnt lgkmcnt(0)
	v_mfma_f32_16x16x32_bf16 v[124:127], v[148:151], v[172:175], v[124:127]
	s_cselect_b32 s7, s0, 0
	s_add_i32 s10, s10, 1
	s_waitcnt lgkmcnt(0)
	v_mfma_f32_16x16x32_bf16 v[120:123], v[144:147], v[172:175], v[120:123]
	s_add_u32 s2, s2, 64
	s_addc_u32 s3, s3, 0
	s_cmpk_lg_i32 s2, 0x800
	v_mfma_f32_16x16x32_bf16 v[116:119], v[136:139], v[172:175], v[116:119]
	s_barrier
	v_mfma_f32_16x16x32_bf16 v[112:115], v[132:135], v[172:175], v[112:115]
	v_mfma_f32_16x16x32_bf16 v[108:111], v[148:151], v[168:171], v[108:111]
	v_mfma_f32_16x16x32_bf16 v[104:107], v[144:147], v[168:171], v[104:107]
	v_mfma_f32_16x16x32_bf16 v[100:103], v[136:139], v[168:171], v[100:103]
	v_mfma_f32_16x16x32_bf16 v[96:99], v[132:135], v[168:171], v[96:99]
	v_mfma_f32_16x16x32_bf16 v[92:95], v[148:151], v[164:167], v[92:95]
	v_mfma_f32_16x16x32_bf16 v[88:91], v[144:147], v[164:167], v[88:91]
	v_mfma_f32_16x16x32_bf16 v[84:87], v[136:139], v[164:167], v[84:87]
	v_mfma_f32_16x16x32_bf16 v[80:83], v[132:135], v[164:167], v[80:83]
	v_mfma_f32_16x16x32_bf16 v[76:79], v[148:151], v[160:163], v[76:79]
	v_mfma_f32_16x16x32_bf16 v[72:75], v[144:147], v[160:163], v[72:75]
	v_mfma_f32_16x16x32_bf16 v[68:71], v[136:139], v[160:163], v[68:71]
	v_mfma_f32_16x16x32_bf16 v[64:67], v[132:135], v[160:163], v[64:67]
	v_mfma_f32_16x16x32_bf16 v[60:63], v[148:151], v[156:159], v[60:63]
	v_mfma_f32_16x16x32_bf16 v[56:59], v[144:147], v[156:159], v[56:59]
	v_mfma_f32_16x16x32_bf16 v[52:55], v[136:139], v[156:159], v[52:55]
	v_mfma_f32_16x16x32_bf16 v[48:51], v[132:135], v[156:159], v[48:51]
	v_mfma_f32_16x16x32_bf16 v[44:47], v[148:151], v[152:155], v[44:47]
	v_mfma_f32_16x16x32_bf16 v[40:43], v[144:147], v[152:155], v[40:43]
	v_mfma_f32_16x16x32_bf16 v[36:39], v[136:139], v[152:155], v[36:39]
	v_mfma_f32_16x16x32_bf16 v[32:35], v[132:135], v[152:155], v[32:35]
	v_mfma_f32_16x16x32_bf16 v[28:31], v[148:151], v[140:143], v[28:31]
	v_mfma_f32_16x16x32_bf16 v[24:27], v[144:147], v[140:143], v[24:27]
	v_mfma_f32_16x16x32_bf16 v[20:23], v[136:139], v[140:143], v[20:23]
	v_mfma_f32_16x16x32_bf16 v[16:19], v[132:135], v[140:143], v[16:19]
	v_mfma_f32_16x16x32_bf16 v[12:15], v[148:151], v[128:131], v[12:15]
	v_mfma_f32_16x16x32_bf16 v[8:11], v[144:147], v[128:131], v[8:11]
	v_mfma_f32_16x16x32_bf16 v[4:7], v[136:139], v[128:131], v[4:7]
	v_mfma_f32_16x16x32_bf16 v[0:3], v[132:135], v[128:131], v[0:3]
	s_cbranch_scc0 .LBB0_132
.LBB0_128:
	s_lshl_b32 s11, s7, 15
	v_or_b32_e32 v132, s11, v211
	v_add3_u32 v128, v132, s20, v212
	s_barrier
	ds_read_b128 v[172:175], v128
	ds_read_b128 v[168:171], v128 offset:1024
	ds_read_b128 v[164:167], v128 offset:2048
	ds_read_b128 v[160:163], v128 offset:3072
	ds_read_b128 v[156:159], v128 offset:4096
	ds_read_b128 v[152:155], v128 offset:5120
	ds_read_b128 v[140:143], v128 offset:6144
	ds_read_b128 v[128:131], v128 offset:7168
	v_add3_u32 v132, v132, s40, v212
	ds_read_b128 v[148:151], v132 offset:16384
	ds_read_b128 v[144:147], v132 offset:17408
	ds_read_b128 v[136:139], v132 offset:18432
	ds_read_b128 v[132:135], v132 offset:19456
	s_cmp_lt_u32 s10, 29
	s_cselect_b64 s[0:1], -1, 0
	s_or_b64 s[12:13], s[8:9], s[0:1]
	s_cbranch_scc1 .Lgk_i1
	s_waitcnt vmcnt(0)
	s_branch .LBB0_127
.Lgk_i1:
	v_lshl_add_u64 v[218:219], v[200:201], 0, s[2:3]
	v_lshl_add_u64 v[220:221], v[196:197], 0, s[2:3]
	s_addk_i32 s11, 0x8000
	v_cndmask_b32_e64 v219, v221, v219, s[0:1]
	v_cndmask_b32_e64 v218, v220, v218, s[0:1]
	v_lshl_add_u64 v[220:221], v[198:199], 0, s[2:3]
	v_lshl_add_u64 v[222:223], v[194:195], 0, s[2:3]
	s_cmp_gt_i32 s7, 0
	v_cndmask_b32_e64 v221, v223, v221, s[0:1]
	v_cndmask_b32_e64 v220, v222, v220, s[0:1]
	s_cselect_b32 s0, s11, 0x18000
	s_add_i32 s0, s15, s0
	s_add_i32 s12, s0, 0x4000
	s_mov_b32 m0, s0
	s_add_i32 s11, s0, 0x2000
	global_load_lds_dwordx4 v[220:221], off
	s_mov_b32 m0, s12
	s_add_i32 s1, s0, 0x6000
	v_lshl_add_u64 v[224:225], v[220:221], 0, s[94:95]
	global_load_lds_dwordx4 v[218:219], off
	s_mov_b32 m0, s11
	v_lshl_add_u64 v[222:223], v[218:219], 0, s[94:95]
	global_load_lds_dwordx4 v[224:225], off
	s_mov_b32 m0, s1
	s_nop 0
	global_load_lds_dwordx4 v[222:223], off
	s_waitcnt vmcnt(8)
	s_branch .LBB0_127

.LBB0_135:
	s_add_i32 s0, s52, 1
	s_cmp_lg_u32 s52, 3
	s_cselect_b32 s52, s0, 0
	s_add_i32 s7, s7, 1
	s_add_u32 s2, s2, 64
	s_addc_u32 s3, s3, 0
	s_cmpk_eq_i32 s2, 0x800
	s_barrier
	s_cbranch_scc1 .LBB0_142
.LBB0_136:
	s_lshl_b32 s10, s52, 15
	v_or_b32_e32 v128, s10, v211
	v_add_u32_e32 v132, v128, v212
	ds_read_b128 v[172:175], v132
	ds_read_b128 v[168:171], v132 offset:1024
	ds_read_b128 v[164:167], v132 offset:2048
	ds_read_b128 v[160:163], v132 offset:3072
	ds_read_b128 v[156:159], v132 offset:4096
	ds_read_b128 v[152:155], v132 offset:5120
	ds_read_b128 v[136:139], v132 offset:6144
	ds_read_b128 v[128:131], v132 offset:7168
	v_add_u32_e32 v132, s41, v132
	ds_read_b128 v[144:147], v132 offset:16384
	ds_read_b128 v[148:151], v132 offset:17408
	ds_read_b128 v[140:143], v132 offset:18432
	ds_read_b128 v[132:135], v132 offset:19456
	s_cmp_lt_u32 s7, 29
	s_cselect_b64 s[0:1], -1, 0
	s_nor_b64 s[12:13], s[8:9], s[0:1]
	s_cbranch_scc1 .LBB0_138
	v_lshl_add_u64 v[194:195], v[186:187], 0, s[2:3]
	v_lshl_add_u64 v[196:197], v[190:191], 0, s[2:3]
	s_addk_i32 s10, 0x8000
	v_cndmask_b32_e64 v195, v197, v195, s[0:1]
	v_cndmask_b32_e64 v194, v196, v194, s[0:1]
	v_lshl_add_u64 v[196:197], v[188:189], 0, s[2:3]
	v_lshl_add_u64 v[198:199], v[192:193], 0, s[2:3]
	s_cmp_gt_i32 s52, 0
	v_cndmask_b32_e64 v197, v199, v197, s[0:1]
	v_cndmask_b32_e64 v196, v198, v196, s[0:1]
	s_cselect_b32 s0, s10, 0x18000
	s_add_i32 s0, s15, s0
	s_add_i32 s11, s0, 0x4000
	s_mov_b32 m0, s0
	s_add_i32 s10, s0, 0x2000
	global_load_lds_dwordx4 v[196:197], off
	s_mov_b32 m0, s11
	s_add_i32 s1, s0, 0x6000
	v_lshl_add_u64 v[200:201], v[196:197], 0, s[94:95]
	global_load_lds_dwordx4 v[194:195], off
	s_mov_b32 m0, s10
	v_lshl_add_u64 v[198:199], v[194:195], 0, s[94:95]
	global_load_lds_dwordx4 v[200:201], off
	s_mov_b32 m0, s1
	s_nop 0
	global_load_lds_dwordx4 v[198:199], off
.LBB0_138:
	s_waitcnt lgkmcnt(0)
	v_mfma_f32_16x16x32_bf16 v[124:127], v[144:147], v[172:175], v[124:127]
	s_waitcnt lgkmcnt(0)
	v_mfma_f32_16x16x32_bf16 v[120:123], v[148:151], v[172:175], v[120:123]
	s_barrier
	v_mfma_f32_16x16x32_bf16 v[116:119], v[140:143], v[172:175], v[116:119]
	v_mfma_f32_16x16x32_bf16 v[112:115], v[132:135], v[172:175], v[112:115]
	v_mfma_f32_16x16x32_bf16 v[108:111], v[144:147], v[168:171], v[108:111]
	v_mfma_f32_16x16x32_bf16 v[104:107], v[148:151], v[168:171], v[104:107]
	v_mfma_f32_16x16x32_bf16 v[100:103], v[140:143], v[168:171], v[100:103]
	v_mfma_f32_16x16x32_bf16 v[96:99], v[132:135], v[168:171], v[96:99]
	v_mfma_f32_16x16x32_bf16 v[92:95], v[144:147], v[164:167], v[92:95]
	v_mfma_f32_16x16x32_bf16 v[88:91], v[148:151], v[164:167], v[88:91]
	v_mfma_f32_16x16x32_bf16 v[84:87], v[140:143], v[164:167], v[84:87]
	v_mfma_f32_16x16x32_bf16 v[80:83], v[132:135], v[164:167], v[80:83]
	v_mfma_f32_16x16x32_bf16 v[76:79], v[144:147], v[160:163], v[76:79]
	v_mfma_f32_16x16x32_bf16 v[72:75], v[148:151], v[160:163], v[72:75]
	v_mfma_f32_16x16x32_bf16 v[68:71], v[140:143], v[160:163], v[68:71]
	v_mfma_f32_16x16x32_bf16 v[64:67], v[132:135], v[160:163], v[64:67]
	v_mfma_f32_16x16x32_bf16 v[60:63], v[144:147], v[156:159], v[60:63]
	v_mfma_f32_16x16x32_bf16 v[56:59], v[148:151], v[156:159], v[56:59]
	v_mfma_f32_16x16x32_bf16 v[52:55], v[140:143], v[156:159], v[52:55]
	v_mfma_f32_16x16x32_bf16 v[48:51], v[132:135], v[156:159], v[48:51]
	v_mfma_f32_16x16x32_bf16 v[44:47], v[144:147], v[152:155], v[44:47]
	v_mfma_f32_16x16x32_bf16 v[40:43], v[148:151], v[152:155], v[40:43]
	v_mfma_f32_16x16x32_bf16 v[36:39], v[140:143], v[152:155], v[36:39]
	v_mfma_f32_16x16x32_bf16 v[32:35], v[132:135], v[152:155], v[32:35]
	v_mfma_f32_16x16x32_bf16 v[28:31], v[144:147], v[136:139], v[28:31]
	v_mfma_f32_16x16x32_bf16 v[24:27], v[148:151], v[136:139], v[24:27]
	v_mfma_f32_16x16x32_bf16 v[20:23], v[140:143], v[136:139], v[20:23]
	v_mfma_f32_16x16x32_bf16 v[16:19], v[132:135], v[136:139], v[16:19]
	v_mfma_f32_16x16x32_bf16 v[12:15], v[144:147], v[128:131], v[12:15]
	v_mfma_f32_16x16x32_bf16 v[8:11], v[148:151], v[128:131], v[8:11]
	v_mfma_f32_16x16x32_bf16 v[4:7], v[140:143], v[128:131], v[4:7]
	v_mfma_f32_16x16x32_bf16 v[0:3], v[132:135], v[128:131], v[0:3]
	s_cmp_lg_u64 s[12:13], 0
	s_cbranch_scc1 .Lgk_w1
	s_waitcnt vmcnt(8)
	s_branch .LBB0_135
